# accumulator zeroing at every GEMM tile start done with 64 v_mov_b64 instead of 128 v_mov_b32 (all GEMM phases), on top of the up-GEMM load-segment recipe
# baseline (speedup 1.0000x reference)
;     __host__ __device__ bool next(int i, Unit& u) const { if (!StaticOrder::next(i, u)) return false; u.pm = nM - 1 - u.pm; return true; }
; template <class Epi, class Sched, bool ALIGN_EPI = false, bool SP2 = false>
; __device__ __forceinline__ void gemm_phase(LAS unsigned char* lds, const Gemm g, const Sched& S, const Epi& E, int wid) {
;     ...
;         const bool has_next = S.next(ui + 1, nxt);
;         const char* nA = has_next ? (const char*)g.A + (size_t)nxt.pm * tstepA + (size_t)nxt.pn * g.a_pn_off : cA; const char* nB = has_next ? (const char*)g.Bt + (size_t)nxt.pn * tstepB : cB;
;     ...
; #pragma unroll
;         for (int a = 0; a < 2; ++a)
; #pragma unroll
;             for (int b = 0; b < 2; ++b)
; #pragma unroll
;                 for (int m = 0; m < 4; ++m)
; #pragma unroll
;                     for (int n = 0; n < 2; ++n) acc[a][b][m][n] = (f32x4){0.f, 0.f, 0.f, 0.f};
;         cur = nxt; cA = nA; cB = nB; ++ui;
.LBB0_184:
	s_ashr_i32 s39, s38, 31
	s_lshl_b64 s[40:41], s[38:39], 20
	s_add_u32 s39, s69, s40
	s_addc_u32 s42, s70, s41
	s_ashr_i32 s37, s36, 31
	s_lshl_b64 s[40:41], s[36:37], 9
	s_add_u32 s40, s39, s40
	s_addc_u32 s41, s42, s41
	s_and_b64 s[42:43], s[34:35], exec
	s_cselect_b32 s39, s41, s49
	s_cselect_b32 s81, s40, s48
	s_lshl_b64 s[42:43], s[36:37], 17
	s_add_u32 s42, s25, s42
	s_addc_u32 s43, s68, s43
	s_and_b64 s[50:51], s[34:35], exec
	v_mov_b32_e32 v0, 0
	s_cselect_b32 s37, s43, s47
	s_cselect_b32 s82, s42, s46
	s_mov_b64 s[54:55], 0
	s_mov_b64 s[50:51], -1
	s_mov_b64 s[52:53], 0
	v_mov_b32_e32 v1, v0
	v_mov_b64_e32 v[2:3], 0
	v_mov_b64_e32 v[4:5], 0
	v_mov_b64_e32 v[6:7], 0
	v_mov_b64_e32 v[8:9], 0
	v_mov_b64_e32 v[10:11], 0
	v_mov_b64_e32 v[16:17], 0
	v_mov_b64_e32 v[18:19], 0
	v_mov_b64_e32 v[24:25], 0
	v_mov_b64_e32 v[26:27], 0
	v_mov_b64_e32 v[32:33], 0
	v_mov_b64_e32 v[34:35], 0
	v_mov_b64_e32 v[40:41], 0
	v_mov_b64_e32 v[42:43], 0
	v_mov_b64_e32 v[48:49], 0
	v_mov_b64_e32 v[50:51], 0
	v_mov_b64_e32 v[12:13], 0
	v_mov_b64_e32 v[14:15], 0
	v_mov_b64_e32 v[20:21], 0
	v_mov_b64_e32 v[22:23], 0
	v_mov_b64_e32 v[28:29], 0
	v_mov_b64_e32 v[30:31], 0
	v_mov_b64_e32 v[36:37], 0
	v_mov_b64_e32 v[38:39], 0
	v_mov_b64_e32 v[44:45], 0
	v_mov_b64_e32 v[46:47], 0
	v_mov_b64_e32 v[52:53], 0
	v_mov_b64_e32 v[54:55], 0
	v_mov_b64_e32 v[56:57], 0
	v_mov_b64_e32 v[58:59], 0
	v_mov_b64_e32 v[60:61], 0
	v_mov_b64_e32 v[62:63], 0
	v_mov_b64_e32 v[64:65], 0
	v_mov_b64_e32 v[66:67], 0
	v_mov_b64_e32 v[68:69], 0
	v_mov_b64_e32 v[70:71], 0
	v_mov_b64_e32 v[72:73], 0
	v_mov_b64_e32 v[74:75], 0
	v_mov_b64_e32 v[80:81], 0
	v_mov_b64_e32 v[82:83], 0
	v_mov_b64_e32 v[88:89], 0
	v_mov_b64_e32 v[90:91], 0
	v_mov_b64_e32 v[96:97], 0
	v_mov_b64_e32 v[98:99], 0
	v_mov_b64_e32 v[104:105], 0
	v_mov_b64_e32 v[106:107], 0
	v_mov_b64_e32 v[112:113], 0
	v_mov_b64_e32 v[114:115], 0
	v_mov_b64_e32 v[76:77], 0
	v_mov_b64_e32 v[78:79], 0
	v_mov_b64_e32 v[84:85], 0
	v_mov_b64_e32 v[86:87], 0
	v_mov_b64_e32 v[92:93], 0
	v_mov_b64_e32 v[94:95], 0
	v_mov_b64_e32 v[100:101], 0
	v_mov_b64_e32 v[102:103], 0
	v_mov_b64_e32 v[108:109], 0
	v_mov_b64_e32 v[110:111], 0
	v_mov_b64_e32 v[116:117], 0
	v_mov_b64_e32 v[118:119], 0
	v_mov_b64_e32 v[120:121], 0
	v_mov_b64_e32 v[122:123], 0
	v_mov_b64_e32 v[124:125], 0
	v_mov_b64_e32 v[126:127], 0

;     __host__ __device__ bool next(int i, Unit& u) const { if (!StaticOrder::next(i, u)) return false; u.pm = nM - 1 - u.pm; return true; }
; template <class Epi, class Sched, bool ALIGN_EPI = false, bool SP2 = false>
; __device__ __forceinline__ void gemm_phase(LAS unsigned char* lds, const Gemm g, const Sched& S, const Epi& E, int wid) {
;     ...
;         const bool has_next = S.next(ui + 1, nxt);
;         const char* nA = has_next ? (const char*)g.A + (size_t)nxt.pm * tstepA + (size_t)nxt.pn * g.a_pn_off : cA; const char* nB = has_next ? (const char*)g.Bt + (size_t)nxt.pn * tstepB : cB;
;     ...
; #pragma unroll
;         for (int a = 0; a < 2; ++a)
; #pragma unroll
;             for (int b = 0; b < 2; ++b)
; #pragma unroll
;                 for (int m = 0; m < 4; ++m)
; #pragma unroll
;                     for (int n = 0; n < 2; ++n) acc[a][b][m][n] = (f32x4){0.f, 0.f, 0.f, 0.f};
;         cur = nxt; cA = nA; cB = nB; ++ui;
.LBB0_202:
	s_ashr_i32 s47, s46, 31
	s_lshl_b64 s[48:49], s[46:47], 20
	s_add_u32 s48, s35, s48
	s_addc_u32 s49, s37, s49
	s_and_b64 s[50:51], s[4:5], exec
	s_cselect_b32 s7, s49, s55
	s_cselect_b32 s47, s48, s54
	s_ashr_i32 s45, s44, 31
	s_lshl_b64 s[50:51], s[44:45], 20
	s_add_u32 s50, s29, s50
	s_addc_u32 s51, s31, s51
	s_and_b64 s[58:59], s[4:5], exec
	s_cselect_b32 s45, s51, s57
	s_cselect_b32 s53, s50, s56
	s_add_u32 s54, s54, 0x80080
	s_addc_u32 s55, s55, 0
	s_add_u32 s72, s56, 0x100
	v_mov_b32_e32 v0, 0
	s_addc_u32 s73, s57, 0
	s_mov_b32 s74, -2
	v_mov_b32_e32 v1, v0
	v_mov_b64_e32 v[2:3], 0
	v_mov_b64_e32 v[4:5], 0
	v_mov_b64_e32 v[6:7], 0
	v_mov_b64_e32 v[16:17], 0
	v_mov_b64_e32 v[18:19], 0
	v_mov_b64_e32 v[20:21], 0
	v_mov_b64_e32 v[22:23], 0
	v_mov_b64_e32 v[32:33], 0
	v_mov_b64_e32 v[34:35], 0
	v_mov_b64_e32 v[36:37], 0
	v_mov_b64_e32 v[38:39], 0
	v_mov_b64_e32 v[48:49], 0
	v_mov_b64_e32 v[50:51], 0
	v_mov_b64_e32 v[52:53], 0
	v_mov_b64_e32 v[54:55], 0
	v_mov_b64_e32 v[8:9], 0
	v_mov_b64_e32 v[10:11], 0
	v_mov_b64_e32 v[12:13], 0
	v_mov_b64_e32 v[14:15], 0
	v_mov_b64_e32 v[24:25], 0
	v_mov_b64_e32 v[26:27], 0
	v_mov_b64_e32 v[28:29], 0
	v_mov_b64_e32 v[30:31], 0
	v_mov_b64_e32 v[40:41], 0
	v_mov_b64_e32 v[42:43], 0
	v_mov_b64_e32 v[44:45], 0
	v_mov_b64_e32 v[46:47], 0
	v_mov_b64_e32 v[56:57], 0
	v_mov_b64_e32 v[58:59], 0
	v_mov_b64_e32 v[60:61], 0
	v_mov_b64_e32 v[62:63], 0
	v_mov_b64_e32 v[64:65], 0
	v_mov_b64_e32 v[66:67], 0
	v_mov_b64_e32 v[68:69], 0
	v_mov_b64_e32 v[70:71], 0
	v_mov_b64_e32 v[80:81], 0
	v_mov_b64_e32 v[82:83], 0
	v_mov_b64_e32 v[84:85], 0
	v_mov_b64_e32 v[86:87], 0
	v_mov_b64_e32 v[96:97], 0
	v_mov_b64_e32 v[98:99], 0
	v_mov_b64_e32 v[100:101], 0
	v_mov_b64_e32 v[102:103], 0
	v_mov_b64_e32 v[112:113], 0
	v_mov_b64_e32 v[114:115], 0
	v_mov_b64_e32 v[116:117], 0
	v_mov_b64_e32 v[118:119], 0
	v_mov_b64_e32 v[72:73], 0
	v_mov_b64_e32 v[74:75], 0
	v_mov_b64_e32 v[76:77], 0
	v_mov_b64_e32 v[78:79], 0
	v_mov_b64_e32 v[88:89], 0
	v_mov_b64_e32 v[90:91], 0
	v_mov_b64_e32 v[92:93], 0
	v_mov_b64_e32 v[94:95], 0
	v_mov_b64_e32 v[104:105], 0
	v_mov_b64_e32 v[106:107], 0
	v_mov_b64_e32 v[108:109], 0
	v_mov_b64_e32 v[110:111], 0
	v_mov_b64_e32 v[120:121], 0
	v_mov_b64_e32 v[122:123], 0
	v_mov_b64_e32 v[124:125], 0
	v_mov_b64_e32 v[126:127], 0

;     __host__ __device__ bool next(int i, Unit& u) const { if (!StaticOrder::next(i, u)) return false; u.pm = nM - 1 - u.pm; return true; }
; template <class Epi, class Sched, bool ALIGN_EPI = false, bool SP2 = false>
; __device__ __forceinline__ void gemm_phase(LAS unsigned char* lds, const Gemm g, const Sched& S, const Epi& E, int wid) {
;     ...
;         const bool has_next = S.next(ui + 1, nxt);
;         const char* nA = has_next ? (const char*)g.A + (size_t)nxt.pm * tstepA + (size_t)nxt.pn * g.a_pn_off : cA; const char* nB = has_next ? (const char*)g.Bt + (size_t)nxt.pn * tstepB : cB;
;     ...
; #pragma unroll
;         for (int a = 0; a < 2; ++a)
; #pragma unroll
;             for (int b = 0; b < 2; ++b)
; #pragma unroll
;                 for (int m = 0; m < 4; ++m)
; #pragma unroll
;                     for (int n = 0; n < 2; ++n) acc[a][b][m][n] = (f32x4){0.f, 0.f, 0.f, 0.f};
;         cur = nxt; cA = nA; cB = nB; ++ui;
.LBB0_396:
	s_ashr_i32 s37, s36, 31
	s_lshl_b64 s[38:39], s[36:37], 20
	s_add_u32 s38, s7, s38
	s_addc_u32 s39, s25, s39
	s_and_b64 s[40:41], s[10:11], exec
	s_cselect_b32 s37, s39, s47
	s_cselect_b32 s43, s38, s46
	s_ashr_i32 s35, s34, 31
	s_lshl_b64 s[40:41], s[34:35], 20
	s_add_u32 s40, s5, s40
	s_addc_u32 s41, s6, s41
	s_and_b64 s[50:51], s[10:11], exec
	s_cselect_b32 s35, s41, s49
	s_cselect_b32 s59, s40, s48
	s_add_u32 s46, s46, 0x80080
	s_addc_u32 s47, s47, 0
	s_add_u32 s60, s48, 0x100
	v_mov_b32_e32 v0, 0
	s_addc_u32 s61, s49, 0
	s_mov_b32 s62, -2
	v_mov_b32_e32 v1, v0
	v_mov_b64_e32 v[2:3], 0
	v_mov_b64_e32 v[4:5], 0
	v_mov_b64_e32 v[6:7], 0
	v_mov_b64_e32 v[16:17], 0
	v_mov_b64_e32 v[18:19], 0
	v_mov_b64_e32 v[20:21], 0
	v_mov_b64_e32 v[22:23], 0
	v_mov_b64_e32 v[32:33], 0
	v_mov_b64_e32 v[34:35], 0
	v_mov_b64_e32 v[36:37], 0
	v_mov_b64_e32 v[38:39], 0
	v_mov_b64_e32 v[48:49], 0
	v_mov_b64_e32 v[50:51], 0
	v_mov_b64_e32 v[52:53], 0
	v_mov_b64_e32 v[54:55], 0
	v_mov_b64_e32 v[8:9], 0
	v_mov_b64_e32 v[10:11], 0
	v_mov_b64_e32 v[12:13], 0
	v_mov_b64_e32 v[14:15], 0
	v_mov_b64_e32 v[24:25], 0
	v_mov_b64_e32 v[26:27], 0
	v_mov_b64_e32 v[28:29], 0
	v_mov_b64_e32 v[30:31], 0
	v_mov_b64_e32 v[40:41], 0
	v_mov_b64_e32 v[42:43], 0
	v_mov_b64_e32 v[44:45], 0
	v_mov_b64_e32 v[46:47], 0
	v_mov_b64_e32 v[56:57], 0
	v_mov_b64_e32 v[58:59], 0
	v_mov_b64_e32 v[60:61], 0
	v_mov_b64_e32 v[62:63], 0
	v_mov_b64_e32 v[64:65], 0
	v_mov_b64_e32 v[66:67], 0
	v_mov_b64_e32 v[68:69], 0
	v_mov_b64_e32 v[70:71], 0
	v_mov_b64_e32 v[80:81], 0
	v_mov_b64_e32 v[82:83], 0
	v_mov_b64_e32 v[84:85], 0
	v_mov_b64_e32 v[86:87], 0
	v_mov_b64_e32 v[96:97], 0
	v_mov_b64_e32 v[98:99], 0
	v_mov_b64_e32 v[100:101], 0
	v_mov_b64_e32 v[102:103], 0
	v_mov_b64_e32 v[112:113], 0
	v_mov_b64_e32 v[114:115], 0
	v_mov_b64_e32 v[116:117], 0
	v_mov_b64_e32 v[118:119], 0
	v_mov_b64_e32 v[72:73], 0
	v_mov_b64_e32 v[74:75], 0
	v_mov_b64_e32 v[76:77], 0
	v_mov_b64_e32 v[78:79], 0
	v_mov_b64_e32 v[88:89], 0
	v_mov_b64_e32 v[90:91], 0
	v_mov_b64_e32 v[92:93], 0
	v_mov_b64_e32 v[94:95], 0
	v_mov_b64_e32 v[104:105], 0
	v_mov_b64_e32 v[106:107], 0
	v_mov_b64_e32 v[108:109], 0
	v_mov_b64_e32 v[110:111], 0
	v_mov_b64_e32 v[120:121], 0
	v_mov_b64_e32 v[122:123], 0
	v_mov_b64_e32 v[124:125], 0
	v_mov_b64_e32 v[126:127], 0

;     __host__ __device__ bool next(int i, Unit& u) const { if (!StaticOrder::next(i, u)) return false; u.pm = nM - 1 - u.pm; return true; }
; template <class Epi, class Sched, bool ALIGN_EPI = false, bool SP2 = false>
; __device__ __forceinline__ void gemm_phase(LAS unsigned char* lds, const Gemm g, const Sched& S, const Epi& E, int wid) {
;     ...
;         const bool has_next = S.next(ui + 1, nxt);
;         const char* nA = has_next ? (const char*)g.A + (size_t)nxt.pm * tstepA + (size_t)nxt.pn * g.a_pn_off : cA; const char* nB = has_next ? (const char*)g.Bt + (size_t)nxt.pn * tstepB : cB;
;     ...
; #pragma unroll
;         for (int a = 0; a < 2; ++a)
; #pragma unroll
;             for (int b = 0; b < 2; ++b)
; #pragma unroll
;                 for (int m = 0; m < 4; ++m)
; #pragma unroll
;                     for (int n = 0; n < 2; ++n) acc[a][b][m][n] = (f32x4){0.f, 0.f, 0.f, 0.f};
;         cur = nxt; cA = nA; cB = nB; ++ui;
.LBB0_487:
	s_ashr_i32 s47, s46, 31
	s_lshl_b64 s[6:7], s[46:47], 20
	s_add_u32 s28, s39, s6
	s_addc_u32 s29, s40, s7
	s_and_b64 s[6:7], s[8:9], exec
	s_cselect_b32 s6, s29, s11
	s_cselect_b32 s7, s28, s10
	s_ashr_i32 s45, s44, 31
	s_lshl_b64 s[34:35], s[44:45], 20
	s_add_u32 s66, s36, s34
	s_addc_u32 s67, s38, s35
	s_and_b64 s[34:35], s[8:9], exec
	s_cselect_b32 s27, s67, s31
	s_cselect_b32 s45, s66, s30
	s_add_u32 s10, s10, 0x80080
	s_addc_u32 s11, s11, 0
	s_add_u32 s47, s30, 0x100
	v_mov_b32_e32 v0, 0
	s_addc_u32 s53, s31, 0
	s_mov_b32 s54, -2
	v_mov_b32_e32 v1, v0
	v_mov_b64_e32 v[2:3], 0
	v_mov_b64_e32 v[4:5], 0
	v_mov_b64_e32 v[6:7], 0
	v_mov_b64_e32 v[16:17], 0
	v_mov_b64_e32 v[18:19], 0
	v_mov_b64_e32 v[20:21], 0
	v_mov_b64_e32 v[22:23], 0
	v_mov_b64_e32 v[32:33], 0
	v_mov_b64_e32 v[34:35], 0
	v_mov_b64_e32 v[36:37], 0
	v_mov_b64_e32 v[38:39], 0
	v_mov_b64_e32 v[48:49], 0
	v_mov_b64_e32 v[50:51], 0
	v_mov_b64_e32 v[52:53], 0
	v_mov_b64_e32 v[54:55], 0
	v_mov_b64_e32 v[8:9], 0
	v_mov_b64_e32 v[10:11], 0
	v_mov_b64_e32 v[12:13], 0
	v_mov_b64_e32 v[14:15], 0
	v_mov_b64_e32 v[24:25], 0
	v_mov_b64_e32 v[26:27], 0
	v_mov_b64_e32 v[28:29], 0
	v_mov_b64_e32 v[30:31], 0
	v_mov_b64_e32 v[40:41], 0
	v_mov_b64_e32 v[42:43], 0
	v_mov_b64_e32 v[44:45], 0
	v_mov_b64_e32 v[46:47], 0
	v_mov_b64_e32 v[56:57], 0
	v_mov_b64_e32 v[58:59], 0
	v_mov_b64_e32 v[60:61], 0
	v_mov_b64_e32 v[62:63], 0
	v_mov_b64_e32 v[64:65], 0
	v_mov_b64_e32 v[66:67], 0
	v_mov_b64_e32 v[68:69], 0
	v_mov_b64_e32 v[70:71], 0
	v_mov_b64_e32 v[80:81], 0
	v_mov_b64_e32 v[82:83], 0
	v_mov_b64_e32 v[84:85], 0
	v_mov_b64_e32 v[86:87], 0
	v_mov_b64_e32 v[96:97], 0
	v_mov_b64_e32 v[98:99], 0
	v_mov_b64_e32 v[100:101], 0
	v_mov_b64_e32 v[102:103], 0
	v_mov_b64_e32 v[112:113], 0
	v_mov_b64_e32 v[114:115], 0
	v_mov_b64_e32 v[116:117], 0
	v_mov_b64_e32 v[118:119], 0
	v_mov_b64_e32 v[72:73], 0
	v_mov_b64_e32 v[74:75], 0
	v_mov_b64_e32 v[76:77], 0
	v_mov_b64_e32 v[78:79], 0
	v_mov_b64_e32 v[88:89], 0
	v_mov_b64_e32 v[90:91], 0
	v_mov_b64_e32 v[92:93], 0
	v_mov_b64_e32 v[94:95], 0
	v_mov_b64_e32 v[104:105], 0
	v_mov_b64_e32 v[106:107], 0
	v_mov_b64_e32 v[108:109], 0
	v_mov_b64_e32 v[110:111], 0
	v_mov_b64_e32 v[120:121], 0
	v_mov_b64_e32 v[122:123], 0
	v_mov_b64_e32 v[124:125], 0
	v_mov_b64_e32 v[126:127], 0

; __global__ void __launch_bounds__(NWAVES * 64, 2) mega_fwd(Args args) {
;     ...
;                   for (int rb = bx * 128 + wave * 16; rb < MTOK; rb += G * 128) {
;                       const bf16_t* ap = XB + (size_t)(rb + fr) * DM + 8 * fq; const bf16_t* bp = WinO + (size_t)(QKV_LD + fr) * DM + 8 * fq;
;                       f32x4 acc = (f32x4){0.f, 0.f, 0.f, 0.f};
.LBB0_529:
	v_ashrrev_i32_e32 v9, 31, v8
	v_lshlrev_b64 v[0:1], 12, v[8:9]
	v_lshl_add_u64 v[12:13], s[12:13], 0, v[0:1]
	v_mov_b32_e32 v0, 0
	s_movk_i32 s5, 0xffe0
	v_mov_b64_e32 v[14:15], v[10:11]
	v_mov_b32_e32 v1, v0
	v_mov_b64_e32 v[2:3], 0

;     __host__ __device__ bool next(int i, Unit& u) const { if (!StaticOrder::next(i, u)) return false; u.pm = nM - 1 - u.pm; return true; }
; template <class Epi, class Sched, bool ALIGN_EPI = false, bool SP2 = false>
; __device__ __forceinline__ void gemm_phase(LAS unsigned char* lds, const Gemm g, const Sched& S, const Epi& E, int wid) {
;     ...
;         const bool has_next = S.next(ui + 1, nxt);
;         const char* nA = has_next ? (const char*)g.A + (size_t)nxt.pm * tstepA + (size_t)nxt.pn * g.a_pn_off : cA; const char* nB = has_next ? (const char*)g.Bt + (size_t)nxt.pn * tstepB : cB;
;     ...
; #pragma unroll
;         for (int a = 0; a < 2; ++a)
; #pragma unroll
;             for (int b = 0; b < 2; ++b)
; #pragma unroll
;                 for (int m = 0; m < 4; ++m)
; #pragma unroll
;                     for (int n = 0; n < 2; ++n) acc[a][b][m][n] = (f32x4){0.f, 0.f, 0.f, 0.f};
;         cur = nxt; cA = nA; cB = nB; ++ui;
.LBB0_880:
	s_ashr_i32 s31, s30, 31
	s_lshl_b64 s[34:35], s[30:31], 20
	s_add_u32 s34, s6, s34
	s_addc_u32 s35, s7, s35
	s_and_b64 s[38:39], s[10:11], exec
	s_cselect_b32 s31, s35, s41
	s_cselect_b32 s54, s34, s40
	s_ashr_i32 s29, s28, 31
	s_lshl_b64 s[38:39], s[28:29], 20
	s_add_u32 s38, s4, s38
	s_addc_u32 s39, s5, s39
	s_and_b64 s[46:47], s[10:11], exec
	s_cselect_b32 s29, s39, s45
	s_cselect_b32 s55, s38, s44
	s_add_u32 s40, s40, 0x80080
	s_addc_u32 s41, s41, 0
	s_add_u32 s56, s44, 0x100
	v_mov_b32_e32 v0, 0
	s_addc_u32 s57, s45, 0
	s_mov_b32 s58, -2
	v_mov_b32_e32 v1, v0
	v_mov_b64_e32 v[2:3], 0
	v_mov_b64_e32 v[4:5], 0
	v_mov_b64_e32 v[6:7], 0
	v_mov_b64_e32 v[16:17], 0
	v_mov_b64_e32 v[18:19], 0
	v_mov_b64_e32 v[20:21], 0
	v_mov_b64_e32 v[22:23], 0
	v_mov_b64_e32 v[32:33], 0
	v_mov_b64_e32 v[34:35], 0
	v_mov_b64_e32 v[36:37], 0
	v_mov_b64_e32 v[38:39], 0
	v_mov_b64_e32 v[48:49], 0
	v_mov_b64_e32 v[50:51], 0
	v_mov_b64_e32 v[52:53], 0
	v_mov_b64_e32 v[54:55], 0
	v_mov_b64_e32 v[8:9], 0
	v_mov_b64_e32 v[10:11], 0
	v_mov_b64_e32 v[12:13], 0
	v_mov_b64_e32 v[14:15], 0
	v_mov_b64_e32 v[24:25], 0
	v_mov_b64_e32 v[26:27], 0
	v_mov_b64_e32 v[28:29], 0
	v_mov_b64_e32 v[30:31], 0
	v_mov_b64_e32 v[40:41], 0
	v_mov_b64_e32 v[42:43], 0
	v_mov_b64_e32 v[44:45], 0
	v_mov_b64_e32 v[46:47], 0
	v_mov_b64_e32 v[56:57], 0
	v_mov_b64_e32 v[58:59], 0
	v_mov_b64_e32 v[60:61], 0
	v_mov_b64_e32 v[62:63], 0
	v_mov_b64_e32 v[64:65], 0
	v_mov_b64_e32 v[66:67], 0
	v_mov_b64_e32 v[68:69], 0
	v_mov_b64_e32 v[70:71], 0
	v_mov_b64_e32 v[80:81], 0
	v_mov_b64_e32 v[82:83], 0
	v_mov_b64_e32 v[84:85], 0
	v_mov_b64_e32 v[86:87], 0
	v_mov_b64_e32 v[96:97], 0
	v_mov_b64_e32 v[98:99], 0
	v_mov_b64_e32 v[100:101], 0
	v_mov_b64_e32 v[102:103], 0
	v_mov_b64_e32 v[112:113], 0
	v_mov_b64_e32 v[114:115], 0
	v_mov_b64_e32 v[116:117], 0
	v_mov_b64_e32 v[118:119], 0
	v_mov_b64_e32 v[72:73], 0
	v_mov_b64_e32 v[74:75], 0
	v_mov_b64_e32 v[76:77], 0
	v_mov_b64_e32 v[78:79], 0
	v_mov_b64_e32 v[88:89], 0
	v_mov_b64_e32 v[90:91], 0
	v_mov_b64_e32 v[92:93], 0
	v_mov_b64_e32 v[94:95], 0
	v_mov_b64_e32 v[104:105], 0
	v_mov_b64_e32 v[106:107], 0
	v_mov_b64_e32 v[108:109], 0
	v_mov_b64_e32 v[110:111], 0
	v_mov_b64_e32 v[120:121], 0
	v_mov_b64_e32 v[122:123], 0
	v_mov_b64_e32 v[124:125], 0
	v_mov_b64_e32 v[126:127], 0
	s_waitcnt vmcnt(0)

;     __host__ __device__ bool next(int i, Unit& u) const { if (!StaticOrder::next(i, u)) return false; u.pm = nM - 1 - u.pm; return true; }
; template <class Epi, class Sched, bool ALIGN_EPI = false, bool SP2 = false>
; __device__ __forceinline__ void gemm_phase(LAS unsigned char* lds, const Gemm g, const Sched& S, const Epi& E, int wid) {
;     ...
;         const bool has_next = S.next(ui + 1, nxt);
;         const char* nA = has_next ? (const char*)g.A + (size_t)nxt.pm * tstepA + (size_t)nxt.pn * g.a_pn_off : cA; const char* nB = has_next ? (const char*)g.Bt + (size_t)nxt.pn * tstepB : cB;
;     ...
; #pragma unroll
;         for (int a = 0; a < 2; ++a)
; #pragma unroll
;             for (int b = 0; b < 2; ++b)
; #pragma unroll
;                 for (int m = 0; m < 4; ++m)
; #pragma unroll
;                     for (int n = 0; n < 2; ++n) acc[a][b][m][n] = (f32x4){0.f, 0.f, 0.f, 0.f};
;         cur = nxt; cA = nA; cB = nB; ++ui;
.LBB0_967:
	s_ashr_i32 s41, s40, 31
	s_lshl_b64 s[42:43], s[40:41], 20
	s_add_u32 s50, s97, s42
	s_addc_u32 s51, s27, s43
	s_and_b64 s[42:43], s[10:11], exec
	s_cselect_b32 s41, s51, s55
	s_cselect_b32 s42, s50, s54
	s_ashr_i32 s93, s92, 31
	s_lshl_b64 s[48:49], s[92:93], 20
	s_add_u32 s52, s6, s48
	s_addc_u32 s53, s7, s49
	s_and_b64 s[48:49], s[10:11], exec
	s_cselect_b32 s43, s53, s57
	s_cselect_b32 s59, s52, s56
	s_add_u32 s60, s56, 0x100
	v_mov_b32_e32 v8, 0
	s_addc_u32 s61, s57, 0
	s_mov_b32 s93, -2
	v_mov_b32_e32 v9, v8
	v_mov_b64_e32 v[10:11], 0
	v_mov_b64_e32 v[64:65], 0
	v_mov_b64_e32 v[66:67], 0
	v_mov_b64_e32 v[12:13], 0
	v_mov_b64_e32 v[14:15], 0
	v_mov_b64_e32 v[68:69], 0
	v_mov_b64_e32 v[70:71], 0
	v_mov_b64_e32 v[0:1], 0
	v_mov_b64_e32 v[2:3], 0
	v_mov_b64_e32 v[76:77], 0
	v_mov_b64_e32 v[78:79], 0
	v_mov_b64_e32 v[20:21], 0
	v_mov_b64_e32 v[22:23], 0
	v_mov_b64_e32 v[84:85], 0
	v_mov_b64_e32 v[86:87], 0
	v_mov_b64_e32 v[16:17], 0
	v_mov_b64_e32 v[18:19], 0
	v_mov_b64_e32 v[72:73], 0
	v_mov_b64_e32 v[74:75], 0
	v_mov_b64_e32 v[24:25], 0
	v_mov_b64_e32 v[26:27], 0
	v_mov_b64_e32 v[80:81], 0
	v_mov_b64_e32 v[82:83], 0
	v_mov_b64_e32 v[4:5], 0
	v_mov_b64_e32 v[6:7], 0
	v_mov_b64_e32 v[88:89], 0
	v_mov_b64_e32 v[90:91], 0
	v_mov_b64_e32 v[28:29], 0
	v_mov_b64_e32 v[30:31], 0
	v_mov_b64_e32 v[92:93], 0
	v_mov_b64_e32 v[94:95], 0
	v_mov_b64_e32 v[40:41], 0
	v_mov_b64_e32 v[42:43], 0
	v_mov_b64_e32 v[96:97], 0
	v_mov_b64_e32 v[98:99], 0
	v_mov_b64_e32 v[44:45], 0
	v_mov_b64_e32 v[46:47], 0
	s_waitcnt vmcnt(0)
	v_mov_b64_e32 v[136:137], 0
	v_mov_b64_e32 v[138:139], 0
	v_mov_b64_e32 v[32:33], 0
	v_mov_b64_e32 v[34:35], 0
	v_mov_b64_e32 v[148:149], 0
	v_mov_b64_e32 v[150:151], 0
	v_mov_b64_e32 v[52:53], 0
	v_mov_b64_e32 v[54:55], 0
	v_mov_b64_e32 v[156:157], 0
	v_mov_b64_e32 v[158:159], 0
	v_mov_b64_e32 v[48:49], 0
	v_mov_b64_e32 v[50:51], 0
	v_mov_b64_e32 v[100:101], 0
	v_mov_b64_e32 v[102:103], 0
	v_mov_b64_e32 v[56:57], 0
	v_mov_b64_e32 v[58:59], 0
	v_mov_b64_e32 v[140:141], 0
	v_mov_b64_e32 v[142:143], 0
	v_mov_b64_e32 v[36:37], 0
	v_mov_b64_e32 v[38:39], 0
	v_mov_b64_e32 v[152:153], 0
	v_mov_b64_e32 v[154:155], 0
	v_mov_b64_e32 v[60:61], 0
	v_mov_b64_e32 v[62:63], 0
	v_mov_b64_e32 v[160:161], 0
	v_mov_b64_e32 v[162:163], 0

;     __host__ __device__ bool next(int i, Unit& u) const { if (!StaticOrder::next(i, u)) return false; u.pm = nM - 1 - u.pm; return true; }
; template <class Epi, class Sched, bool ALIGN_EPI = false, bool SP2 = false>
; __device__ __forceinline__ void gemm_phase(LAS unsigned char* lds, const Gemm g, const Sched& S, const Epi& E, int wid) {
;     ...
;         const bool has_next = S.next(ui + 1, nxt);
;         const char* nA = has_next ? (const char*)g.A + (size_t)nxt.pm * tstepA + (size_t)nxt.pn * g.a_pn_off : cA; const char* nB = has_next ? (const char*)g.Bt + (size_t)nxt.pn * tstepB : cB;
;     ...
; #pragma unroll
;         for (int a = 0; a < 2; ++a)
; #pragma unroll
;             for (int b = 0; b < 2; ++b)
; #pragma unroll
;                 for (int m = 0; m < 4; ++m)
; #pragma unroll
;                     for (int n = 0; n < 2; ++n) acc[a][b][m][n] = (f32x4){0.f, 0.f, 0.f, 0.f};
;         cur = nxt; cA = nA; cB = nB; ++ui;
.LBB0_1150:
	s_add_u32 s56, s40, 0x100
	v_mov_b32_e32 v0, 0
	s_addc_u32 s57, s41, 0
	s_mov_b32 s58, -2
	v_mov_b32_e32 v1, v0
	v_mov_b64_e32 v[2:3], 0
	v_mov_b64_e32 v[4:5], 0
	v_mov_b64_e32 v[6:7], 0
	v_mov_b64_e32 v[16:17], 0
	v_mov_b64_e32 v[18:19], 0
	v_mov_b64_e32 v[20:21], 0
	v_mov_b64_e32 v[22:23], 0
	v_mov_b64_e32 v[32:33], 0
	v_mov_b64_e32 v[34:35], 0
	v_mov_b64_e32 v[36:37], 0
	v_mov_b64_e32 v[38:39], 0
	v_mov_b64_e32 v[48:49], 0
	v_mov_b64_e32 v[50:51], 0
	v_mov_b64_e32 v[52:53], 0
	v_mov_b64_e32 v[54:55], 0
	v_mov_b64_e32 v[8:9], 0
	v_mov_b64_e32 v[10:11], 0
	v_mov_b64_e32 v[12:13], 0
	v_mov_b64_e32 v[14:15], 0
	v_mov_b64_e32 v[24:25], 0
	v_mov_b64_e32 v[26:27], 0
	v_mov_b64_e32 v[28:29], 0
	v_mov_b64_e32 v[30:31], 0
	v_mov_b64_e32 v[40:41], 0
	v_mov_b64_e32 v[42:43], 0
	v_mov_b64_e32 v[44:45], 0
	v_mov_b64_e32 v[46:47], 0
	v_mov_b64_e32 v[56:57], 0
	v_mov_b64_e32 v[58:59], 0
	v_mov_b64_e32 v[60:61], 0
	v_mov_b64_e32 v[62:63], 0
	v_mov_b64_e32 v[64:65], 0
	v_mov_b64_e32 v[66:67], 0
	v_mov_b64_e32 v[68:69], 0
	v_mov_b64_e32 v[70:71], 0
	v_mov_b64_e32 v[80:81], 0
	v_mov_b64_e32 v[82:83], 0
	v_mov_b64_e32 v[84:85], 0
	v_mov_b64_e32 v[86:87], 0
	v_mov_b64_e32 v[96:97], 0
	v_mov_b64_e32 v[98:99], 0
	v_mov_b64_e32 v[100:101], 0
	v_mov_b64_e32 v[102:103], 0
	v_mov_b64_e32 v[112:113], 0
	v_mov_b64_e32 v[114:115], 0
	v_mov_b64_e32 v[116:117], 0
	v_mov_b64_e32 v[118:119], 0
	v_mov_b64_e32 v[72:73], 0
	v_mov_b64_e32 v[74:75], 0
	v_mov_b64_e32 v[76:77], 0
	v_mov_b64_e32 v[78:79], 0
	v_mov_b64_e32 v[88:89], 0
	v_mov_b64_e32 v[90:91], 0
	v_mov_b64_e32 v[92:93], 0
	v_mov_b64_e32 v[94:95], 0
	v_mov_b64_e32 v[104:105], 0
	v_mov_b64_e32 v[106:107], 0
	v_mov_b64_e32 v[108:109], 0
	v_mov_b64_e32 v[110:111], 0
	v_mov_b64_e32 v[120:121], 0
	v_mov_b64_e32 v[122:123], 0
	v_mov_b64_e32 v[124:125], 0
	v_mov_b64_e32 v[126:127], 0
	s_waitcnt vmcnt(0)
